# static priority raise for waves 4-7 around the attention tile loop (on top of 4-phase L3a)
# baseline (speedup 1.0000x reference)
.LBB0_1065:
	s_setprio 0
	v_mov_b32_e32 v0, v33
	s_getreg_b32 s2, hwreg(HW_REG_HW_ID, 0, 6)
	s_lshl_b32 s2, s2, 2
	s_and_b32 s2, s2, 0xfc
	s_add_i32 s2, s2, 0
	s_add_i32 s2, s2, 0x21100
	v_mov_b32_e32 v1, s2
	ds_read_b32 v1, v1
	v_mbcnt_lo_u32_b32 v0, -1, v0
	v_mbcnt_hi_u32_b32 v0, -1, v0
	s_mov_b64 s[2:3], 0
	v_lshlrev_b32_e32 v36, 16, v203
	s_waitcnt lgkmcnt(0)
	v_lshl_or_b32 v2, v1, 6, v0
	s_add_u32 s2, s76, s2
	s_addc_u32 s3, s77, s3
	s_add_i32 s96, s96, s87
	v_and_or_b32 v0, v2, 31, s96
	v_or_b32_e32 v32, s97, v0
	v_lshlrev_b64 v[0:1], 12, v[32:33]
	v_lshl_add_u64 v[0:1], s[2:3], 0, v[0:1]
	v_lshrrev_b32_e32 v2, 2, v2
	v_lshl_add_u64 v[0:1], s[84:85], 1, v[0:1]
	v_and_b32_e32 v32, 8, v2
	v_lshl_add_u64 v[2:3], v[0:1], 0, v[32:33]
	s_mov_b64 s[2:3], 0x25e51000
	v_lshl_add_u64 v[0:1], v[2:3], 0, s[2:3]
	s_mov_b32 s2, 0x25e51000
	v_add_co_u32_e32 v4, vcc, s2, v2
	v_and_b32_e32 v37, 0xffff0000, v203
	s_nop 0
	v_addc_co_u32_e32 v5, vcc, 0, v3, vcc
	global_load_dwordx2 v[34:35], v[4:5], off
	global_load_dwordx2 v[30:31], v[0:1], off offset:16
	global_load_dwordx2 v[28:29], v[0:1], off offset:32
	global_load_dwordx2 v[26:27], v[0:1], off offset:48
	global_load_dwordx2 v[24:25], v[0:1], off offset:64
	global_load_dwordx2 v[22:23], v[0:1], off offset:80
	global_load_dwordx2 v[20:21], v[0:1], off offset:96
	global_load_dwordx2 v[18:19], v[0:1], off offset:112
	global_load_dwordx2 v[16:17], v[0:1], off offset:128
	global_load_dwordx2 v[14:15], v[0:1], off offset:144
	global_load_dwordx2 v[12:13], v[0:1], off offset:160
	global_load_dwordx2 v[10:11], v[0:1], off offset:176
	global_load_dwordx2 v[8:9], v[0:1], off offset:192
	global_load_dwordx2 v[6:7], v[0:1], off offset:208
	global_load_dwordx2 v[4:5], v[0:1], off offset:224
	s_nop 0
	global_load_dwordx2 v[0:1], v[0:1], off offset:240
	s_mov_b32 s2, 0x29e51000
	v_add_co_u32_e32 v2, vcc, s2, v2
	s_waitcnt vmcnt(0)
	v_lshlrev_b32_e32 v38, 16, v34
	v_mul_f32_e32 v32, 0xbfb8aa3b, v38
	v_exp_f32_e32 v32, v32
	v_and_b32_e32 v39, 0xffff0000, v34
	v_addc_co_u32_e32 v3, vcc, 0, v3, vcc
	v_add_f32_e32 v32, 1.0, v32
	v_rcp_f32_e32 v40, v32
	v_mul_f32_e32 v32, 0xbfb8aa3b, v39
	v_exp_f32_e32 v32, v32
	s_nop 0
	v_add_f32_e32 v32, 1.0, v32
	v_rcp_f32_e32 v41, v32
	s_nop 0
	v_pk_mul_f32 v[38:39], v[40:41], v[38:39]
	s_nop 0
	v_pk_mul_f32 v[36:37], v[38:39], v[36:37]
	v_lshlrev_b32_e32 v38, 16, v35
	v_mul_f32_e32 v32, 0xbfb8aa3b, v38
	v_exp_f32_e32 v32, v32
	v_and_b32_e32 v39, 0xffff0000, v35
	v_cvt_pk_bf16_f32 v34, v36, v37
	v_lshlrev_b32_e32 v36, 16, v202
	v_add_f32_e32 v32, 1.0, v32
	v_rcp_f32_e32 v40, v32
	v_mul_f32_e32 v32, 0xbfb8aa3b, v39
	v_exp_f32_e32 v32, v32
	v_and_b32_e32 v37, 0xffff0000, v202
	v_add_f32_e32 v32, 1.0, v32
	v_rcp_f32_e32 v41, v32
	s_nop 0
	v_pk_mul_f32 v[38:39], v[40:41], v[38:39]
	s_nop 0
	v_pk_mul_f32 v[36:37], v[38:39], v[36:37]
	s_nop 0
	v_cvt_pk_bf16_f32 v35, v36, v37
	v_lshlrev_b32_e32 v36, 16, v30
	v_and_b32_e32 v37, 0xffff0000, v30
	v_mul_f32_e32 v30, 0xbfb8aa3b, v36
	v_exp_f32_e32 v30, v30
	global_store_dwordx2 v[2:3], v[34:35], off
	v_lshlrev_b32_e32 v34, 16, v201
	v_and_b32_e32 v35, 0xffff0000, v201
	v_add_f32_e32 v30, 1.0, v30
	v_rcp_f32_e32 v38, v30
	v_mul_f32_e32 v30, 0xbfb8aa3b, v37
	v_exp_f32_e32 v30, v30
	s_nop 0
	v_add_f32_e32 v30, 1.0, v30
	v_rcp_f32_e32 v39, v30
	s_nop 0
	v_pk_mul_f32 v[36:37], v[38:39], v[36:37]
	s_nop 0
	v_pk_mul_f32 v[34:35], v[36:37], v[34:35]
	v_lshlrev_b32_e32 v36, 16, v31
	v_and_b32_e32 v37, 0xffff0000, v31
	v_mul_f32_e32 v31, 0xbfb8aa3b, v36
	v_exp_f32_e32 v31, v31
	v_cvt_pk_bf16_f32 v30, v34, v35
	v_lshlrev_b32_e32 v34, 16, v200
	v_and_b32_e32 v35, 0xffff0000, v200
	v_add_f32_e32 v31, 1.0, v31
	v_rcp_f32_e32 v38, v31
	v_mul_f32_e32 v31, 0xbfb8aa3b, v37
	v_exp_f32_e32 v31, v31
	s_nop 0
	v_add_f32_e32 v31, 1.0, v31
	v_rcp_f32_e32 v39, v31
	s_nop 0
	v_pk_mul_f32 v[36:37], v[38:39], v[36:37]
	s_nop 0
	v_pk_mul_f32 v[34:35], v[36:37], v[34:35]
	s_nop 0
	v_cvt_pk_bf16_f32 v31, v34, v35
	v_lshlrev_b32_e32 v34, 16, v28
	v_and_b32_e32 v35, 0xffff0000, v28
	v_mul_f32_e32 v28, 0xbfb8aa3b, v34
	v_exp_f32_e32 v28, v28
	global_store_dwordx2 v[2:3], v[30:31], off offset:16
	v_lshlrev_b32_e32 v30, 16, v199
	v_and_b32_e32 v31, 0xffff0000, v199
	v_add_f32_e32 v28, 1.0, v28
	v_rcp_f32_e32 v36, v28
	v_mul_f32_e32 v28, 0xbfb8aa3b, v35
	v_exp_f32_e32 v28, v28
	s_nop 0
	v_add_f32_e32 v28, 1.0, v28
	v_rcp_f32_e32 v37, v28
	s_nop 0
	v_pk_mul_f32 v[34:35], v[36:37], v[34:35]
	s_nop 0
	v_pk_mul_f32 v[30:31], v[34:35], v[30:31]
	v_lshlrev_b32_e32 v34, 16, v29
	v_and_b32_e32 v35, 0xffff0000, v29
	v_mul_f32_e32 v29, 0xbfb8aa3b, v34
	v_exp_f32_e32 v29, v29
	v_cvt_pk_bf16_f32 v28, v30, v31
	v_lshlrev_b32_e32 v30, 16, v198
	v_and_b32_e32 v31, 0xffff0000, v198
	v_add_f32_e32 v29, 1.0, v29
	v_rcp_f32_e32 v36, v29
	v_mul_f32_e32 v29, 0xbfb8aa3b, v35
	v_exp_f32_e32 v29, v29
	s_nop 0
	v_add_f32_e32 v29, 1.0, v29
	v_rcp_f32_e32 v37, v29
	s_nop 0
	v_pk_mul_f32 v[34:35], v[36:37], v[34:35]
	s_nop 0
	v_pk_mul_f32 v[30:31], v[34:35], v[30:31]
	s_nop 0
	v_cvt_pk_bf16_f32 v29, v30, v31
	v_lshlrev_b32_e32 v30, 16, v26
	v_and_b32_e32 v31, 0xffff0000, v26
	v_mul_f32_e32 v26, 0xbfb8aa3b, v30
	v_exp_f32_e32 v26, v26
	global_store_dwordx2 v[2:3], v[28:29], off offset:32
	v_lshlrev_b32_e32 v28, 16, v197
	v_and_b32_e32 v29, 0xffff0000, v197
	v_add_f32_e32 v26, 1.0, v26
	v_rcp_f32_e32 v34, v26
	v_mul_f32_e32 v26, 0xbfb8aa3b, v31
	v_exp_f32_e32 v26, v26
	s_nop 0
	v_add_f32_e32 v26, 1.0, v26
	v_rcp_f32_e32 v35, v26
	s_nop 0
	v_pk_mul_f32 v[30:31], v[34:35], v[30:31]
	s_nop 0
	v_pk_mul_f32 v[28:29], v[30:31], v[28:29]
	v_lshlrev_b32_e32 v30, 16, v27
	v_and_b32_e32 v31, 0xffff0000, v27
	v_mul_f32_e32 v27, 0xbfb8aa3b, v30
	v_exp_f32_e32 v27, v27
	v_cvt_pk_bf16_f32 v26, v28, v29
	v_lshlrev_b32_e32 v28, 16, v196
	v_and_b32_e32 v29, 0xffff0000, v196
	v_add_f32_e32 v27, 1.0, v27
	v_rcp_f32_e32 v34, v27
	v_mul_f32_e32 v27, 0xbfb8aa3b, v31
	v_exp_f32_e32 v27, v27
	s_nop 0
	v_add_f32_e32 v27, 1.0, v27
	v_rcp_f32_e32 v35, v27
	s_nop 0
	v_pk_mul_f32 v[30:31], v[34:35], v[30:31]
	s_nop 0
	v_pk_mul_f32 v[28:29], v[30:31], v[28:29]
	s_nop 0
	v_cvt_pk_bf16_f32 v27, v28, v29
	v_lshlrev_b32_e32 v28, 16, v24
	v_and_b32_e32 v29, 0xffff0000, v24
	v_mul_f32_e32 v24, 0xbfb8aa3b, v28
	v_exp_f32_e32 v24, v24
	global_store_dwordx2 v[2:3], v[26:27], off offset:48
	v_lshlrev_b32_e32 v26, 16, v195
	v_and_b32_e32 v27, 0xffff0000, v195
	v_add_f32_e32 v24, 1.0, v24
	v_rcp_f32_e32 v30, v24
	v_mul_f32_e32 v24, 0xbfb8aa3b, v29
	v_exp_f32_e32 v24, v24
	s_nop 0
	v_add_f32_e32 v24, 1.0, v24
	v_rcp_f32_e32 v31, v24
	s_nop 0
	v_pk_mul_f32 v[28:29], v[30:31], v[28:29]
	s_nop 0
	v_pk_mul_f32 v[26:27], v[28:29], v[26:27]
	v_lshlrev_b32_e32 v28, 16, v25
	v_and_b32_e32 v29, 0xffff0000, v25
	v_mul_f32_e32 v25, 0xbfb8aa3b, v28
	v_exp_f32_e32 v25, v25
	v_cvt_pk_bf16_f32 v24, v26, v27
	v_lshlrev_b32_e32 v26, 16, v194
	v_and_b32_e32 v27, 0xffff0000, v194
	v_add_f32_e32 v25, 1.0, v25
	v_rcp_f32_e32 v30, v25
	v_mul_f32_e32 v25, 0xbfb8aa3b, v29
	v_exp_f32_e32 v25, v25
	s_nop 0
	v_add_f32_e32 v25, 1.0, v25
	v_rcp_f32_e32 v31, v25
	s_nop 0
	v_pk_mul_f32 v[28:29], v[30:31], v[28:29]
	s_nop 0
	v_pk_mul_f32 v[26:27], v[28:29], v[26:27]
	s_nop 0
	v_cvt_pk_bf16_f32 v25, v26, v27
	v_lshlrev_b32_e32 v26, 16, v22
	v_and_b32_e32 v27, 0xffff0000, v22
	v_mul_f32_e32 v22, 0xbfb8aa3b, v26
	v_exp_f32_e32 v22, v22
	global_store_dwordx2 v[2:3], v[24:25], off offset:64
	v_lshlrev_b32_e32 v24, 16, v193
	v_and_b32_e32 v25, 0xffff0000, v193
	v_add_f32_e32 v22, 1.0, v22
	v_rcp_f32_e32 v28, v22
	v_mul_f32_e32 v22, 0xbfb8aa3b, v27
	v_exp_f32_e32 v22, v22
	s_nop 0
	v_add_f32_e32 v22, 1.0, v22
	v_rcp_f32_e32 v29, v22
	s_nop 0
	v_pk_mul_f32 v[26:27], v[28:29], v[26:27]
	s_nop 0
	v_pk_mul_f32 v[24:25], v[26:27], v[24:25]
	v_lshlrev_b32_e32 v26, 16, v23
	v_and_b32_e32 v27, 0xffff0000, v23
	v_mul_f32_e32 v23, 0xbfb8aa3b, v26
	v_exp_f32_e32 v23, v23
	v_cvt_pk_bf16_f32 v22, v24, v25
	v_lshlrev_b32_e32 v24, 16, v192
	v_and_b32_e32 v25, 0xffff0000, v192
	v_add_f32_e32 v23, 1.0, v23
	v_rcp_f32_e32 v28, v23
	v_mul_f32_e32 v23, 0xbfb8aa3b, v27
	v_exp_f32_e32 v23, v23
	s_nop 0
	v_add_f32_e32 v23, 1.0, v23
	v_rcp_f32_e32 v29, v23
	s_nop 0
	v_pk_mul_f32 v[26:27], v[28:29], v[26:27]
	s_nop 0
	v_pk_mul_f32 v[24:25], v[26:27], v[24:25]
	s_nop 0
	v_cvt_pk_bf16_f32 v23, v24, v25
	v_lshlrev_b32_e32 v24, 16, v20
	v_and_b32_e32 v25, 0xffff0000, v20
	v_mul_f32_e32 v20, 0xbfb8aa3b, v24
	v_exp_f32_e32 v20, v20
	global_store_dwordx2 v[2:3], v[22:23], off offset:80
	v_lshlrev_b32_e32 v22, 16, v191
	v_and_b32_e32 v23, 0xffff0000, v191
	v_add_f32_e32 v20, 1.0, v20
	v_rcp_f32_e32 v26, v20
	v_mul_f32_e32 v20, 0xbfb8aa3b, v25
	v_exp_f32_e32 v20, v20
	s_nop 0
	v_add_f32_e32 v20, 1.0, v20
	v_rcp_f32_e32 v27, v20
	s_nop 0
	v_pk_mul_f32 v[24:25], v[26:27], v[24:25]
	s_nop 0
	v_pk_mul_f32 v[22:23], v[24:25], v[22:23]
	v_lshlrev_b32_e32 v24, 16, v21
	v_and_b32_e32 v25, 0xffff0000, v21
	v_mul_f32_e32 v21, 0xbfb8aa3b, v24
	v_exp_f32_e32 v21, v21
	v_cvt_pk_bf16_f32 v20, v22, v23
	v_lshlrev_b32_e32 v22, 16, v190
	v_and_b32_e32 v23, 0xffff0000, v190
	v_add_f32_e32 v21, 1.0, v21
	v_rcp_f32_e32 v26, v21
	v_mul_f32_e32 v21, 0xbfb8aa3b, v25
	v_exp_f32_e32 v21, v21
	s_nop 0
	v_add_f32_e32 v21, 1.0, v21
	v_rcp_f32_e32 v27, v21
	s_nop 0
	v_pk_mul_f32 v[24:25], v[26:27], v[24:25]
	s_nop 0
	v_pk_mul_f32 v[22:23], v[24:25], v[22:23]
	s_nop 0
	v_cvt_pk_bf16_f32 v21, v22, v23
	v_lshlrev_b32_e32 v22, 16, v18
	v_and_b32_e32 v23, 0xffff0000, v18
	v_mul_f32_e32 v18, 0xbfb8aa3b, v22
	v_exp_f32_e32 v18, v18
	global_store_dwordx2 v[2:3], v[20:21], off offset:96
	v_lshlrev_b32_e32 v20, 16, v189
	v_and_b32_e32 v21, 0xffff0000, v189
	v_add_f32_e32 v18, 1.0, v18
	v_rcp_f32_e32 v24, v18
	v_mul_f32_e32 v18, 0xbfb8aa3b, v23
	v_exp_f32_e32 v18, v18
	s_nop 0
	v_add_f32_e32 v18, 1.0, v18
	v_rcp_f32_e32 v25, v18
	s_nop 0
	v_pk_mul_f32 v[22:23], v[24:25], v[22:23]
	s_nop 0
	v_pk_mul_f32 v[20:21], v[22:23], v[20:21]
	v_lshlrev_b32_e32 v22, 16, v19
	v_and_b32_e32 v23, 0xffff0000, v19
	v_mul_f32_e32 v19, 0xbfb8aa3b, v22
	v_exp_f32_e32 v19, v19
	v_cvt_pk_bf16_f32 v18, v20, v21
	v_lshlrev_b32_e32 v20, 16, v188
	v_and_b32_e32 v21, 0xffff0000, v188
	v_add_f32_e32 v19, 1.0, v19
	v_rcp_f32_e32 v24, v19
	v_mul_f32_e32 v19, 0xbfb8aa3b, v23
	v_exp_f32_e32 v19, v19
	s_nop 0
	v_add_f32_e32 v19, 1.0, v19
	v_rcp_f32_e32 v25, v19
	s_nop 0
	v_pk_mul_f32 v[22:23], v[24:25], v[22:23]
	s_nop 0
	v_pk_mul_f32 v[20:21], v[22:23], v[20:21]
	s_nop 0
	v_cvt_pk_bf16_f32 v19, v20, v21
	v_lshlrev_b32_e32 v20, 16, v16
	v_and_b32_e32 v21, 0xffff0000, v16
	v_mul_f32_e32 v16, 0xbfb8aa3b, v20
	v_exp_f32_e32 v16, v16
	global_store_dwordx2 v[2:3], v[18:19], off offset:112
	v_lshlrev_b32_e32 v18, 16, v187
	v_and_b32_e32 v19, 0xffff0000, v187
	v_add_f32_e32 v16, 1.0, v16
	v_rcp_f32_e32 v22, v16
	v_mul_f32_e32 v16, 0xbfb8aa3b, v21
	v_exp_f32_e32 v16, v16
	s_nop 0
	v_add_f32_e32 v16, 1.0, v16
	v_rcp_f32_e32 v23, v16
	s_nop 0
	v_pk_mul_f32 v[20:21], v[22:23], v[20:21]
	s_nop 0
	v_pk_mul_f32 v[18:19], v[20:21], v[18:19]
	v_lshlrev_b32_e32 v20, 16, v17
	v_and_b32_e32 v21, 0xffff0000, v17
	v_mul_f32_e32 v17, 0xbfb8aa3b, v20
	v_exp_f32_e32 v17, v17
	v_cvt_pk_bf16_f32 v16, v18, v19
	v_lshlrev_b32_e32 v18, 16, v186
	v_and_b32_e32 v19, 0xffff0000, v186
	v_add_f32_e32 v17, 1.0, v17
	v_rcp_f32_e32 v22, v17
	v_mul_f32_e32 v17, 0xbfb8aa3b, v21
	v_exp_f32_e32 v17, v17
	s_nop 0
	v_add_f32_e32 v17, 1.0, v17
	v_rcp_f32_e32 v23, v17
	s_nop 0
	v_pk_mul_f32 v[20:21], v[22:23], v[20:21]
	s_nop 0
	v_pk_mul_f32 v[18:19], v[20:21], v[18:19]
	s_nop 0
	v_cvt_pk_bf16_f32 v17, v18, v19
	v_lshlrev_b32_e32 v18, 16, v14
	v_and_b32_e32 v19, 0xffff0000, v14
	v_mul_f32_e32 v14, 0xbfb8aa3b, v18
	v_exp_f32_e32 v14, v14
	global_store_dwordx2 v[2:3], v[16:17], off offset:128
	v_lshlrev_b32_e32 v16, 16, v185
	v_and_b32_e32 v17, 0xffff0000, v185
	v_add_f32_e32 v14, 1.0, v14
	v_rcp_f32_e32 v20, v14
	v_mul_f32_e32 v14, 0xbfb8aa3b, v19
	v_exp_f32_e32 v14, v14
	s_nop 0
	v_add_f32_e32 v14, 1.0, v14
	v_rcp_f32_e32 v21, v14
	s_nop 0
	v_pk_mul_f32 v[18:19], v[20:21], v[18:19]
	s_nop 0
	v_pk_mul_f32 v[16:17], v[18:19], v[16:17]
	v_lshlrev_b32_e32 v18, 16, v15
	v_and_b32_e32 v19, 0xffff0000, v15
	v_mul_f32_e32 v15, 0xbfb8aa3b, v18
	v_exp_f32_e32 v15, v15
	v_cvt_pk_bf16_f32 v14, v16, v17
	v_lshlrev_b32_e32 v16, 16, v184
	v_and_b32_e32 v17, 0xffff0000, v184
	v_add_f32_e32 v15, 1.0, v15
	v_rcp_f32_e32 v20, v15
	v_mul_f32_e32 v15, 0xbfb8aa3b, v19
	v_exp_f32_e32 v15, v15
	s_nop 0
	v_add_f32_e32 v15, 1.0, v15
	v_rcp_f32_e32 v21, v15
	s_nop 0
	v_pk_mul_f32 v[18:19], v[20:21], v[18:19]
	s_nop 0
	v_pk_mul_f32 v[16:17], v[18:19], v[16:17]
	s_nop 0
	v_cvt_pk_bf16_f32 v15, v16, v17
	v_lshlrev_b32_e32 v16, 16, v12
	v_and_b32_e32 v17, 0xffff0000, v12
	v_mul_f32_e32 v12, 0xbfb8aa3b, v16
	v_exp_f32_e32 v12, v12
	global_store_dwordx2 v[2:3], v[14:15], off offset:144
	v_lshlrev_b32_e32 v14, 16, v183
	v_and_b32_e32 v15, 0xffff0000, v183
	v_add_f32_e32 v12, 1.0, v12
	v_rcp_f32_e32 v18, v12
	v_mul_f32_e32 v12, 0xbfb8aa3b, v17
	v_exp_f32_e32 v12, v12
	s_nop 0
	v_add_f32_e32 v12, 1.0, v12
	v_rcp_f32_e32 v19, v12
	s_nop 0
	v_pk_mul_f32 v[16:17], v[18:19], v[16:17]
	s_nop 0
	v_pk_mul_f32 v[14:15], v[16:17], v[14:15]
	v_lshlrev_b32_e32 v16, 16, v13
	v_and_b32_e32 v17, 0xffff0000, v13
	v_mul_f32_e32 v13, 0xbfb8aa3b, v16
	v_exp_f32_e32 v13, v13
	v_cvt_pk_bf16_f32 v12, v14, v15
	v_lshlrev_b32_e32 v14, 16, v182
	v_and_b32_e32 v15, 0xffff0000, v182
	v_add_f32_e32 v13, 1.0, v13
	v_rcp_f32_e32 v18, v13
	v_mul_f32_e32 v13, 0xbfb8aa3b, v17
	v_exp_f32_e32 v13, v13
	s_nop 0
	v_add_f32_e32 v13, 1.0, v13
	v_rcp_f32_e32 v19, v13
	s_nop 0
	v_pk_mul_f32 v[16:17], v[18:19], v[16:17]
	s_nop 0
	v_pk_mul_f32 v[14:15], v[16:17], v[14:15]
	s_nop 0
	v_cvt_pk_bf16_f32 v13, v14, v15
	v_lshlrev_b32_e32 v14, 16, v10
	v_and_b32_e32 v15, 0xffff0000, v10
	v_mul_f32_e32 v10, 0xbfb8aa3b, v14
	v_exp_f32_e32 v10, v10
	global_store_dwordx2 v[2:3], v[12:13], off offset:160
	v_lshlrev_b32_e32 v12, 16, v181
	v_and_b32_e32 v13, 0xffff0000, v181
	v_add_f32_e32 v10, 1.0, v10
	v_rcp_f32_e32 v16, v10
	v_mul_f32_e32 v10, 0xbfb8aa3b, v15
	v_exp_f32_e32 v10, v10
	s_nop 0
	v_add_f32_e32 v10, 1.0, v10
	v_rcp_f32_e32 v17, v10
	s_nop 0
	v_pk_mul_f32 v[14:15], v[16:17], v[14:15]
	s_nop 0
	v_pk_mul_f32 v[12:13], v[14:15], v[12:13]
	v_lshlrev_b32_e32 v14, 16, v11
	v_and_b32_e32 v15, 0xffff0000, v11
	v_mul_f32_e32 v11, 0xbfb8aa3b, v14
	v_exp_f32_e32 v11, v11
	v_cvt_pk_bf16_f32 v10, v12, v13
	v_lshlrev_b32_e32 v12, 16, v180
	v_and_b32_e32 v13, 0xffff0000, v180
	v_add_f32_e32 v11, 1.0, v11
	v_rcp_f32_e32 v16, v11
	v_mul_f32_e32 v11, 0xbfb8aa3b, v15
	v_exp_f32_e32 v11, v11
	s_nop 0
	v_add_f32_e32 v11, 1.0, v11
	v_rcp_f32_e32 v17, v11
	s_nop 0
	v_pk_mul_f32 v[14:15], v[16:17], v[14:15]
	s_nop 0
	v_pk_mul_f32 v[12:13], v[14:15], v[12:13]
	s_nop 0
	v_cvt_pk_bf16_f32 v11, v12, v13
	v_lshlrev_b32_e32 v12, 16, v8
	v_and_b32_e32 v13, 0xffff0000, v8
	v_mul_f32_e32 v8, 0xbfb8aa3b, v12
	v_exp_f32_e32 v8, v8
	global_store_dwordx2 v[2:3], v[10:11], off offset:176
	v_lshlrev_b32_e32 v10, 16, v177
	v_and_b32_e32 v11, 0xffff0000, v177
	v_add_f32_e32 v8, 1.0, v8
	v_rcp_f32_e32 v14, v8
	v_mul_f32_e32 v8, 0xbfb8aa3b, v13
	v_exp_f32_e32 v8, v8
	s_nop 0
	v_add_f32_e32 v8, 1.0, v8
	v_rcp_f32_e32 v15, v8
	s_nop 0
	v_pk_mul_f32 v[12:13], v[14:15], v[12:13]
	s_nop 0
	v_pk_mul_f32 v[10:11], v[12:13], v[10:11]
	v_lshlrev_b32_e32 v12, 16, v9
	v_and_b32_e32 v13, 0xffff0000, v9
	v_mul_f32_e32 v9, 0xbfb8aa3b, v12
	v_exp_f32_e32 v9, v9
	v_cvt_pk_bf16_f32 v8, v10, v11
	v_lshlrev_b32_e32 v10, 16, v176
	v_and_b32_e32 v11, 0xffff0000, v176
	v_add_f32_e32 v9, 1.0, v9
	v_rcp_f32_e32 v14, v9
	v_mul_f32_e32 v9, 0xbfb8aa3b, v13
	v_exp_f32_e32 v9, v9
	s_nop 0
	v_add_f32_e32 v9, 1.0, v9
	v_rcp_f32_e32 v15, v9
	s_nop 0
	v_pk_mul_f32 v[12:13], v[14:15], v[12:13]
	s_nop 0
	v_pk_mul_f32 v[10:11], v[12:13], v[10:11]
	s_nop 0
	v_cvt_pk_bf16_f32 v9, v10, v11
	v_lshlrev_b32_e32 v10, 16, v6
	v_and_b32_e32 v11, 0xffff0000, v6
	v_mul_f32_e32 v6, 0xbfb8aa3b, v10
	v_exp_f32_e32 v6, v6
	global_store_dwordx2 v[2:3], v[8:9], off offset:192
	v_lshlrev_b32_e32 v8, 16, v175
	v_and_b32_e32 v9, 0xffff0000, v175
	v_add_f32_e32 v6, 1.0, v6
	v_rcp_f32_e32 v12, v6
	v_mul_f32_e32 v6, 0xbfb8aa3b, v11
	v_exp_f32_e32 v6, v6
	s_nop 0
	v_add_f32_e32 v6, 1.0, v6
	v_rcp_f32_e32 v13, v6
	s_nop 0
	v_pk_mul_f32 v[10:11], v[12:13], v[10:11]
	s_nop 0
	v_pk_mul_f32 v[8:9], v[10:11], v[8:9]
	v_lshlrev_b32_e32 v10, 16, v7
	v_and_b32_e32 v11, 0xffff0000, v7
	v_mul_f32_e32 v7, 0xbfb8aa3b, v10
	v_exp_f32_e32 v7, v7
	v_cvt_pk_bf16_f32 v6, v8, v9
	v_lshlrev_b32_e32 v8, 16, v174
	v_and_b32_e32 v9, 0xffff0000, v174
	v_add_f32_e32 v7, 1.0, v7
	v_rcp_f32_e32 v12, v7
	v_mul_f32_e32 v7, 0xbfb8aa3b, v11
	v_exp_f32_e32 v7, v7
	s_nop 0
	v_add_f32_e32 v7, 1.0, v7
	v_rcp_f32_e32 v13, v7
	s_nop 0
	v_pk_mul_f32 v[10:11], v[12:13], v[10:11]
	s_nop 0
	v_pk_mul_f32 v[8:9], v[10:11], v[8:9]
	s_nop 0
	v_cvt_pk_bf16_f32 v7, v8, v9
	v_lshlrev_b32_e32 v8, 16, v4
	v_and_b32_e32 v9, 0xffff0000, v4
	v_mul_f32_e32 v4, 0xbfb8aa3b, v8
	v_exp_f32_e32 v4, v4
	global_store_dwordx2 v[2:3], v[6:7], off offset:208
	v_lshlrev_b32_e32 v6, 16, v173
	v_and_b32_e32 v7, 0xffff0000, v173
	v_add_f32_e32 v4, 1.0, v4
	v_rcp_f32_e32 v10, v4
	v_mul_f32_e32 v4, 0xbfb8aa3b, v9
	v_exp_f32_e32 v4, v4
	s_nop 0
	v_add_f32_e32 v4, 1.0, v4
	v_rcp_f32_e32 v11, v4
	s_nop 0
	v_pk_mul_f32 v[8:9], v[10:11], v[8:9]
	s_nop 0
	v_pk_mul_f32 v[6:7], v[8:9], v[6:7]
	v_lshlrev_b32_e32 v8, 16, v5
	v_and_b32_e32 v9, 0xffff0000, v5
	v_mul_f32_e32 v5, 0xbfb8aa3b, v8
	v_exp_f32_e32 v5, v5
	v_cvt_pk_bf16_f32 v4, v6, v7
	v_lshlrev_b32_e32 v6, 16, v172
	v_and_b32_e32 v7, 0xffff0000, v172
	v_add_f32_e32 v5, 1.0, v5
	v_rcp_f32_e32 v10, v5
	v_mul_f32_e32 v5, 0xbfb8aa3b, v9
	v_exp_f32_e32 v5, v5
	s_nop 0
	v_add_f32_e32 v5, 1.0, v5
	v_rcp_f32_e32 v11, v5
	s_nop 0
	v_pk_mul_f32 v[8:9], v[10:11], v[8:9]
	s_nop 0
	v_pk_mul_f32 v[6:7], v[8:9], v[6:7]
	s_nop 0
	v_cvt_pk_bf16_f32 v5, v6, v7
	v_lshlrev_b32_e32 v6, 16, v0
	v_and_b32_e32 v7, 0xffff0000, v0
	v_mul_f32_e32 v0, 0xbfb8aa3b, v6
	v_exp_f32_e32 v0, v0
	global_store_dwordx2 v[2:3], v[4:5], off offset:224
	v_lshlrev_b32_e32 v4, 16, v171
	v_and_b32_e32 v5, 0xffff0000, v171
	v_add_f32_e32 v0, 1.0, v0
	v_rcp_f32_e32 v8, v0
	v_mul_f32_e32 v0, 0xbfb8aa3b, v7
	v_exp_f32_e32 v0, v0
	s_nop 0
	v_add_f32_e32 v0, 1.0, v0
	v_rcp_f32_e32 v9, v0
	s_nop 0
	v_pk_mul_f32 v[6:7], v[8:9], v[6:7]
	s_nop 0
	v_pk_mul_f32 v[4:5], v[6:7], v[4:5]
	v_lshlrev_b32_e32 v6, 16, v1
	v_and_b32_e32 v7, 0xffff0000, v1
	v_mul_f32_e32 v1, 0xbfb8aa3b, v6
	v_exp_f32_e32 v1, v1
	v_cvt_pk_bf16_f32 v0, v4, v5
	v_lshlrev_b32_e32 v4, 16, v170
	v_and_b32_e32 v5, 0xffff0000, v170
	v_add_f32_e32 v1, 1.0, v1
	v_rcp_f32_e32 v8, v1
	v_mul_f32_e32 v1, 0xbfb8aa3b, v7
	v_exp_f32_e32 v1, v1
	s_nop 0
	v_add_f32_e32 v1, 1.0, v1
	v_rcp_f32_e32 v9, v1
	s_nop 0
	v_pk_mul_f32 v[6:7], v[8:9], v[6:7]
	s_nop 0
	v_pk_mul_f32 v[4:5], v[6:7], v[4:5]
	s_nop 0
	v_cvt_pk_bf16_f32 v1, v4, v5
	global_store_dwordx2 v[2:3], v[0:1], off offset:240

.LBB0_1102:
	s_waitcnt vmcnt(0)
	v_pk_mul_f32 v[0:1], v[66:67], v[0:1] op_sel_hi:[0,1]
	v_cvt_pk_bf16_f32 v177, v0, v1
	v_pk_mul_f32 v[0:1], v[66:67], v[2:3] op_sel_hi:[0,1]
	v_cvt_pk_bf16_f32 v176, v0, v1
	v_pk_mul_f32 v[0:1], v[66:67], v[4:5] op_sel_hi:[0,1]
	v_cvt_pk_bf16_f32 v175, v0, v1
	v_pk_mul_f32 v[0:1], v[66:67], v[6:7] op_sel_hi:[0,1]
	v_cvt_pk_bf16_f32 v174, v0, v1
	v_pk_mul_f32 v[0:1], v[66:67], v[8:9] op_sel_hi:[0,1]
	v_cvt_pk_bf16_f32 v173, v0, v1
	v_pk_mul_f32 v[0:1], v[66:67], v[10:11] op_sel_hi:[0,1]
	v_pk_mul_f32 v[50:51], v[50:51], v[66:67] op_sel_hi:[1,0]
	v_pk_mul_f32 v[34:35], v[34:35], v[66:67] op_sel_hi:[1,0]
	v_pk_mul_f32 v[16:17], v[16:17], v[66:67] op_sel_hi:[1,0]
	v_cvt_pk_bf16_f32 v172, v0, v1
	v_pk_mul_f32 v[0:1], v[66:67], v[12:13] op_sel_hi:[0,1]
	v_cvt_pk_bf16_f32 v203, v50, v51
	v_pk_mul_f32 v[50:51], v[52:53], v[66:67] op_sel_hi:[1,0]
	v_cvt_pk_bf16_f32 v195, v34, v35
	v_pk_mul_f32 v[34:35], v[36:37], v[66:67] op_sel_hi:[1,0]
	v_cvt_pk_bf16_f32 v187, v16, v17
	v_pk_mul_f32 v[16:17], v[18:19], v[66:67] op_sel_hi:[1,0]
	v_cvt_pk_bf16_f32 v171, v0, v1
	v_pk_mul_f32 v[0:1], v[66:67], v[14:15] op_sel_hi:[0,1]
	v_cvt_pk_bf16_f32 v202, v50, v51
	v_pk_mul_f32 v[50:51], v[54:55], v[66:67] op_sel_hi:[1,0]
	v_cvt_pk_bf16_f32 v194, v34, v35
	v_pk_mul_f32 v[34:35], v[38:39], v[66:67] op_sel_hi:[1,0]
	v_cvt_pk_bf16_f32 v186, v16, v17
	v_pk_mul_f32 v[16:17], v[20:21], v[66:67] op_sel_hi:[1,0]
	v_cvt_pk_bf16_f32 v170, v0, v1
	s_waitcnt vmcnt(0) lgkmcnt(0)
	s_barrier
	v_mov_b32_e32 v1, s45
	s_lshl_b32 s14, s92, 18
	v_cvt_pk_bf16_f32 v201, v50, v51
	v_pk_mul_f32 v[50:51], v[56:57], v[66:67] op_sel_hi:[1,0]
	v_cvt_pk_bf16_f32 v193, v34, v35
	v_pk_mul_f32 v[34:35], v[40:41], v[66:67] op_sel_hi:[1,0]
	v_cvt_pk_bf16_f32 v185, v16, v17
	v_pk_mul_f32 v[16:17], v[22:23], v[66:67] op_sel_hi:[1,0]
	ds_read_b32 v1, v1
	s_mov_b64 s[2:3], 0x11341000
	v_cvt_pk_bf16_f32 v200, v50, v51
	v_pk_mul_f32 v[50:51], v[58:59], v[66:67] op_sel_hi:[1,0]
	v_cvt_pk_bf16_f32 v192, v34, v35
	v_pk_mul_f32 v[34:35], v[42:43], v[66:67] op_sel_hi:[1,0]
	v_cvt_pk_bf16_f32 v184, v16, v17
	v_pk_mul_f32 v[16:17], v[24:25], v[66:67] op_sel_hi:[1,0]
	s_add_u32 s15, s80, 0x31e51000
	v_lshl_add_u32 v0, v126, 2, 0
	v_mov_b32_e32 v2, s86
	v_lshl_add_u64 v[162:163], v[68:69], 0, s[2:3]
	v_cvt_pk_bf16_f32 v199, v50, v51
	v_pk_mul_f32 v[50:51], v[60:61], v[66:67] op_sel_hi:[1,0]
	v_cvt_pk_bf16_f32 v191, v34, v35
	v_pk_mul_f32 v[34:35], v[44:45], v[66:67] op_sel_hi:[1,0]
	v_cvt_pk_bf16_f32 v183, v16, v17
	v_pk_mul_f32 v[16:17], v[26:27], v[66:67] op_sel_hi:[1,0]
	s_addc_u32 s16, s81, 0
	v_add_u32_e32 v0, 0x1ad00, v0
	ds_read_b32 v204, v2 offset:508
	ds_read_b32 v205, v0
	s_lshl_b32 s3, 2, s79
	v_cvt_pk_bf16_f32 v198, v50, v51
	v_pk_mul_f32 v[50:51], v[62:63], v[66:67] op_sel_hi:[1,0]
	v_cvt_pk_bf16_f32 v190, v34, v35
	v_pk_mul_f32 v[34:35], v[46:47], v[66:67] op_sel_hi:[1,0]
	v_cvt_pk_bf16_f32 v182, v16, v17
	v_pk_mul_f32 v[16:17], v[28:29], v[66:67] op_sel_hi:[1,0]
	s_add_i32 s3, s3, -1
	v_cvt_pk_bf16_f32 v197, v50, v51
	v_pk_mul_f32 v[50:51], v[64:65], v[66:67] op_sel_hi:[1,0]
	v_cvt_pk_bf16_f32 v189, v34, v35
	v_pk_mul_f32 v[34:35], v[48:49], v[66:67] op_sel_hi:[1,0]
	v_cvt_pk_bf16_f32 v181, v16, v17
	v_pk_mul_f32 v[16:17], v[30:31], v[66:67] op_sel_hi:[1,0]
	s_cmp_gt_u32 s93, 31
	v_mov_b32_e32 v66, v33
	v_mov_b32_e32 v67, v33
	v_mov_b32_e32 v80, v33
	v_mov_b32_e32 v81, v33
	v_cvt_pk_bf16_f32 v196, v50, v51
	v_cvt_pk_bf16_f32 v188, v34, v35
	s_waitcnt lgkmcnt(0)
	v_readfirstlane_b32 s2, v1
	s_cselect_b32 s3, s3, -2
	v_sub_u32_e64 v0, s79, 8 clamp
	v_mov_b32_e32 v68, v33
	v_mov_b32_e32 v69, v33
	v_mov_b32_e32 v70, v33
	v_mov_b32_e32 v71, v33
	v_mov_b32_e32 v72, v33
	v_mov_b32_e32 v73, v33
	v_mov_b32_e32 v74, v33
	v_mov_b32_e32 v75, v33
	v_mov_b32_e32 v76, v33
	v_mov_b32_e32 v77, v33
	v_mov_b32_e32 v78, v33
	v_mov_b32_e32 v79, v33
	v_mov_b64_e32 v[96:97], v[80:81]
	v_mov_b64_e32 v[50:51], v[66:67]
	v_mov_b64_e32 v[34:35], v[66:67]
	v_cvt_pk_bf16_f32 v180, v16, v17
	s_add_i32 s17, s96, 0xffffff41
	v_lshl_add_u32 v206, v124, 10, v127
	s_and_b32 s18, s2, s3
	v_readfirstlane_b32 s19, v0
	s_or_b32 s20, s96, 63
	v_sub_u32_e32 v207, v125, v128
	s_mov_b32 s21, 0
	s_mov_b32 s23, 1
	v_mov_b32_e32 v208, 0
	v_mov_b32_e32 v209, 0xc69c4000
	v_lshlrev_b64 v[164:165], 1, v[32:33]
	v_mov_b64_e32 v[94:95], v[78:79]
	v_mov_b64_e32 v[92:93], v[76:77]
	v_mov_b64_e32 v[90:91], v[74:75]
	v_mov_b64_e32 v[88:89], v[72:73]
	v_mov_b64_e32 v[86:87], v[70:71]
	v_mov_b64_e32 v[84:85], v[68:69]
	v_mov_b64_e32 v[82:83], v[66:67]
	v_mov_b64_e32 v[52:53], v[68:69]
	v_mov_b64_e32 v[54:55], v[70:71]
	v_mov_b64_e32 v[56:57], v[72:73]
	v_mov_b64_e32 v[58:59], v[74:75]
	v_mov_b64_e32 v[60:61], v[76:77]
	v_mov_b64_e32 v[62:63], v[78:79]
	v_mov_b64_e32 v[64:65], v[80:81]
	v_mov_b64_e32 v[36:37], v[68:69]
	v_mov_b64_e32 v[38:39], v[70:71]
	v_mov_b64_e32 v[40:41], v[72:73]
	v_mov_b64_e32 v[42:43], v[74:75]
	v_mov_b64_e32 v[44:45], v[76:77]
	v_mov_b64_e32 v[46:47], v[78:79]
	v_mov_b64_e32 v[48:49], v[80:81]
	s_mov_b32 s10, 0
	s_lshr_b32 s2, s62, 13
	s_cmp_eq_u32 s2, 0
	s_cbranch_scc1 .Latt_noprio
	s_setprio 1
.Latt_noprio:
.LBB0_1103:
	s_cmp_lg_u32 s23, 1
	s_cselect_b64 s[8:9], -1, 0
	s_mov_b64 s[2:3], -1
	s_and_b64 vcc, exec, s[8:9]
	s_cbranch_vccnz .LBB0_1114
	s_lshl_b32 s2, -2, s10
	s_and_b32 s6, s18, s2
	s_cmp_lt_i32 s10, 31
	s_cselect_b64 s[2:3], -1, 0
	s_cmp_lg_u32 s6, 0
	s_cselect_b64 s[4:5], -1, 0
	s_and_b64 s[2:3], s[2:3], s[4:5]
	s_ff1_i32_b32 s4, s6
	s_and_b64 s[2:3], s[2:3], exec
	s_cselect_b32 s22, 1, 2
	s_cselect_b32 s4, s4, s19
	s_cbranch_execz .LBB0_1115
